# MLA exp/PV group interleave + DMA issues spread in S burst; pool-diff rewrite; NA bias loads hoisted
# speedup vs baseline: 1.0354x; 1.0019x over previous
.LBB0_253:
	s_andn2_b64 vcc, exec, s[10:11]
	s_cbranch_vccnz .LBB0_271
	v_add_u32_e32 v240, v170, v173
	ds_read_b32 v240, v240 offset:50020
	v_add_u32_e32 v241, v170, v177
	ds_read_b32 v241, v241 offset:50020
	v_add_u32_e32 v242, v170, v181
	ds_read_b32 v242, v242 offset:50020
	v_add_u32_e32 v243, v170, v185
	ds_read_b32 v243, v243 offset:50020
	v_add_u32_e32 v244, v170, v189
	ds_read_b32 v244, v244 offset:50080
	v_add_u32_e32 v245, v170, v193
	ds_read_b32 v245, v245 offset:50080
	v_add_u32_e32 v246, v170, v214
	ds_read_b32 v246, v246 offset:50020
	v_add_u32_e32 v247, v170, v218
	ds_read_b32 v247, v247 offset:50020
	v_add_u32_e32 v0, v170, v169
	v_add_u32_e32 v3, v170, v171
	v_add_u32_e32 v124, v170, v172
	ds_read_b32 v2, v0 offset:50020
	ds_read_b32 v3, v3 offset:50020
	ds_read_b32 v0, v124 offset:50020
	s_waitcnt lgkmcnt(3)
	v_mov_b32_e32 v134, 0xf149f2ca
	v_mov_b32_e32 v136, 0xf149f2ca
	s_mov_b64 s[10:11], exec
	v_readlane_b32 s12, v224, 26
	v_readlane_b32 s13, v224, 27
	s_and_b64 s[12:13], s[10:11], s[12:13]
	s_mov_b64 exec, s[12:13]
	s_cbranch_execz .LBB0_256
	v_readlane_b32 s12, v224, 28
	v_readlane_b32 s13, v224, 29
	s_nop 0
	v_add_f32_e32 v108, v108, v240
	v_cndmask_b32_e64 v136, v205, v108, s[12:13]
.LBB0_256:
	s_or_b64 exec, exec, s[10:11]
	v_add_u32_e32 v108, v170, v174
	v_add_u32_e32 v124, v170, v175
	v_add_u32_e32 v125, v170, v176
	ds_read_b32 v128, v108 offset:50020
	ds_read_b32 v129, v124 offset:50020
	ds_read_b32 v108, v125 offset:50020
	s_mov_b64 s[10:11], exec
	v_readlane_b32 s12, v224, 42
	v_readlane_b32 s13, v224, 43
	s_and_b64 s[12:13], s[10:11], s[12:13]
	s_mov_b64 exec, s[12:13]
	s_cbranch_execz .LBB0_258
	v_readlane_b32 s12, v224, 44
	v_readlane_b32 s13, v224, 45
	s_nop 0
	v_add_f32_e32 v112, v112, v241
	v_cndmask_b32_e64 v134, v205, v112, s[12:13]
.LBB0_258:
	s_or_b64 exec, exec, s[10:11]
	v_add_u32_e32 v112, v170, v178
	v_add_u32_e32 v124, v170, v179
	v_add_u32_e32 v125, v170, v180
	ds_read_b32 v138, v112 offset:50020
	ds_read_b32 v139, v124 offset:50020
	ds_read_b32 v112, v125 offset:50020
	v_mov_b32_e32 v140, 0xf149f2ca
	v_mov_b32_e32 v142, 0xf149f2ca
	s_mov_b64 s[10:11], exec
	v_readlane_b32 s12, v224, 58
	v_readlane_b32 s13, v224, 59
	s_and_b64 s[12:13], s[10:11], s[12:13]
	s_mov_b64 exec, s[12:13]
	s_cbranch_execz .LBB0_260
	v_readlane_b32 s12, v224, 60
	v_readlane_b32 s13, v224, 61
	s_nop 0
	v_add_f32_e32 v120, v120, v242
	v_cndmask_b32_e64 v142, v205, v120, s[12:13]
.LBB0_260:
	s_or_b64 exec, exec, s[10:11]
	v_add_u32_e32 v120, v170, v182
	v_add_u32_e32 v124, v170, v183
	v_add_u32_e32 v125, v170, v184
	ds_read_b32 v156, v120 offset:50020
	ds_read_b32 v157, v124 offset:50020
	ds_read_b32 v120, v125 offset:50020
	s_mov_b64 s[10:11], exec
	v_readlane_b32 s12, v221, 10
	v_readlane_b32 s13, v221, 11
	s_and_b64 s[12:13], s[10:11], s[12:13]
	s_mov_b64 exec, s[12:13]
	s_cbranch_execz .LBB0_262
	v_readlane_b32 s12, v221, 12
	v_readlane_b32 s13, v221, 13
	s_nop 0
	v_add_f32_e32 v116, v116, v243
	v_cndmask_b32_e64 v140, v205, v116, s[12:13]
.LBB0_262:
	s_or_b64 exec, exec, s[10:11]
	v_add_u32_e32 v116, v170, v186
	v_add_u32_e32 v124, v170, v187
	v_add_u32_e32 v125, v170, v188
	ds_read_b32 v158, v116 offset:50084
	ds_read_b32 v159, v124 offset:50088
	ds_read_b32 v116, v125 offset:50092
	v_mov_b32_e32 v124, 0xf149f2ca
	v_mov_b32_e32 v126, 0xf149f2ca
	s_mov_b64 s[10:11], exec
	v_readlane_b32 s12, v221, 24
	v_readlane_b32 s13, v221, 25
	s_and_b64 s[12:13], s[10:11], s[12:13]
	s_mov_b64 exec, s[12:13]
	s_cbranch_execz .LBB0_264
	v_readlane_b32 s12, v221, 26
	v_readlane_b32 s13, v221, 27
	s_nop 0
	v_add_f32_e32 v68, v68, v244
	v_cndmask_b32_e64 v126, v205, v68, s[12:13]
.LBB0_264:
	s_or_b64 exec, exec, s[10:11]
	v_add_u32_e32 v68, v170, v190
	v_add_u32_e32 v125, v170, v191
	v_add_u32_e32 v127, v170, v192
	ds_read_b32 v160, v68 offset:50020
	ds_read_b32 v161, v125 offset:50020
	ds_read_b32 v68, v127 offset:50020
	s_mov_b64 s[10:11], exec
	v_readlane_b32 s12, v221, 40
	v_readlane_b32 s13, v221, 41
	s_and_b64 s[12:13], s[10:11], s[12:13]
	s_mov_b64 exec, s[12:13]
	s_cbranch_execz .LBB0_266
	v_readlane_b32 s12, v221, 42
	v_readlane_b32 s13, v221, 43
	s_nop 0
	v_add_f32_e32 v72, v72, v245
	v_cndmask_b32_e64 v124, v205, v72, s[12:13]
.LBB0_266:
	s_or_b64 exec, exec, s[10:11]
	v_add_u32_e32 v72, v170, v194
	v_add_u32_e32 v125, v170, v195
	v_add_u32_e32 v127, v170, v213
	ds_read_b32 v162, v72 offset:50020
	ds_read_b32 v163, v125 offset:50020
	ds_read_b32 v72, v127 offset:50020
	v_mov_b32_e32 v130, 0xf149f2ca
	v_mov_b32_e32 v132, 0xf149f2ca
	s_and_saveexec_b64 s[10:11], s[0:1]
	s_cbranch_execz .LBB0_268
	v_readlane_b32 s12, v221, 50
	v_readlane_b32 s13, v221, 51
	s_nop 0
	v_add_f32_e32 v64, v64, v246
	v_cndmask_b32_e64 v132, v205, v64, s[12:13]
.LBB0_268:
	s_or_b64 exec, exec, s[10:11]
	v_add_u32_e32 v64, v170, v215
	v_add_u32_e32 v125, v170, v216
	v_add_u32_e32 v127, v170, v217
	ds_read_b32 v144, v64 offset:50020
	ds_read_b32 v145, v125 offset:50020
	ds_read_b32 v64, v127 offset:50020
	s_and_saveexec_b64 s[10:11], s[38:39]
	s_cbranch_execz .LBB0_270
	v_readlane_b32 s12, v221, 52
	v_readlane_b32 s13, v221, 53
	s_nop 0
	v_add_f32_e32 v60, v60, v247
	v_cndmask_b32_e64 v130, v205, v60, s[12:13]

	.amdhsa_kernel _Z4mega6Params
		.amdhsa_group_segment_fixed_size 0
		.amdhsa_private_segment_fixed_size 0
		.amdhsa_kernarg_size 472
		.amdhsa_user_sgpr_count 2
		.amdhsa_user_sgpr_dispatch_ptr 0
		.amdhsa_user_sgpr_queue_ptr 0
		.amdhsa_user_sgpr_kernarg_segment_ptr 1
		.amdhsa_user_sgpr_dispatch_id 0
		.amdhsa_user_sgpr_kernarg_preload_length 0
		.amdhsa_user_sgpr_kernarg_preload_offset 0
		.amdhsa_user_sgpr_private_segment_size 0
		.amdhsa_uses_dynamic_stack 0
		.amdhsa_enable_private_segment 0
		.amdhsa_system_sgpr_workgroup_id_x 1
		.amdhsa_system_sgpr_workgroup_id_y 0
		.amdhsa_system_sgpr_workgroup_id_z 0
		.amdhsa_system_sgpr_workgroup_info 0
		.amdhsa_system_vgpr_workitem_id 2
		.amdhsa_next_free_vgpr 248
		.amdhsa_next_free_sgpr 102
		.amdhsa_accum_offset 248
		.amdhsa_reserve_vcc 1
		.amdhsa_float_round_mode_32 0
		.amdhsa_float_round_mode_16_64 0
		.amdhsa_float_denorm_mode_32 3
		.amdhsa_float_denorm_mode_16_64 3
		.amdhsa_dx10_clamp 1
		.amdhsa_ieee_mode 1
		.amdhsa_fp16_overflow 0
		.amdhsa_tg_split 0
		.amdhsa_exception_fp_ieee_invalid_op 0
		.amdhsa_exception_fp_denorm_src 0
		.amdhsa_exception_fp_ieee_div_zero 0
		.amdhsa_exception_fp_ieee_overflow 0
		.amdhsa_exception_fp_ieee_underflow 0
		.amdhsa_exception_fp_ieee_inexact 0
		.amdhsa_exception_int_div_zero 0
	.end_amdhsa_kernel

amdhsa.kernels:
  - .agpr_count:     0
    .args:
      - .offset:         0
        .size:           216
        .value_kind:     by_value
      - .offset:         216
        .size:           4
        .value_kind:     hidden_block_count_x
      - .offset:         220
        .size:           4
        .value_kind:     hidden_block_count_y
      - .offset:         224
        .size:           4
        .value_kind:     hidden_block_count_z
      - .offset:         228
        .size:           2
        .value_kind:     hidden_group_size_x
      - .offset:         230
        .size:           2
        .value_kind:     hidden_group_size_y
      - .offset:         232
        .size:           2
        .value_kind:     hidden_group_size_z
      - .offset:         234
        .size:           2
        .value_kind:     hidden_remainder_x
      - .offset:         236
        .size:           2
        .value_kind:     hidden_remainder_y
      - .offset:         238
        .size:           2
        .value_kind:     hidden_remainder_z
      - .offset:         256
        .size:           8
        .value_kind:     hidden_global_offset_x
      - .offset:         264
        .size:           8
        .value_kind:     hidden_global_offset_y
      - .offset:         272
        .size:           8
        .value_kind:     hidden_global_offset_z
      - .offset:         280
        .size:           2
        .value_kind:     hidden_grid_dims
      - .offset:         304
        .size:           8
        .value_kind:     hidden_multigrid_sync_arg
      - .offset:         336
        .size:           4
        .value_kind:     hidden_dynamic_lds_size
    .group_segment_fixed_size: 0
    .kernarg_segment_align: 8
    .kernarg_segment_size: 472
    .language:       OpenCL C
    .language_version:
      - 2
      - 0
    .max_flat_workgroup_size: 256
    .name:           _Z4mega6Params
    .private_segment_fixed_size: 0
    .sgpr_count:     108
    .sgpr_spill_count: 249
    .symbol:         _Z4mega6Params.kd
    .uniform_work_group_size: 1
    .uses_dynamic_stack: false
    .vgpr_count:     248
    .vgpr_spill_count: 0
    .wavefront_size: 64
